# p0 rmsnorm row loop: norm weight loaded once outside the loop, next row's x loads prefetched one iteration ahead (removes 8 serialized load+store-ack waits per row)
# baseline (speedup 1.0000x reference)
; DI void phase_prep(const Params& P, unsigned char* smem) {
;     ...
;     for (int row = blockIdx.x * 8 + wave; row < NTOK; row += gridDim.x * 8) {
;         const f32x4* xr = (const f32x4*)(P.x + (size_t)row * DM);
;         f32x4 v[8]; float s = 0.f;
; #pragma unroll
;         for (int j = 0; j < 8; ++j) { v[j] = xr[lane + 64 * j]; s += v[j][0] * v[j][0] + v[j][1] * v[j][1] + v[j][2] * v[j][2] + v[j][3] * v[j][3]; }
;         s = wave_sum(s);
;         const float rstd = 1.f / sqrtf(s * (1.f / DM) + EPSF);
.LBB0_19:
	s_or_b64 exec, exec, s[2:3]
	v_mov_b32_e32 v12, v215
	s_lshl_b32 s33, s6, 3
	v_ashrrev_i32_e32 v13, 6, v12
	v_add_u32_e32 v16, s33, v13
	s_mov_b32 s0, 0x8000
	v_and_b32_e32 v14, 63, v12
	v_cmp_gt_i32_e32 vcc, s0, v16
	v_mbcnt_lo_u32_b32 v173, -1, 0
	s_and_saveexec_b64 s[4:5], vcc
	s_cbranch_execz .LBB0_22
	v_mbcnt_hi_u32_b32 v0, -1, v173
	v_and_b32_e32 v1, 64, v0
	v_add_u32_e32 v1, 64, v1
	v_xor_b32_e32 v2, 1, v0
	v_cmp_lt_i32_e32 vcc, v2, v1
	v_mov_b32_e32 v19, 0
	v_lshlrev_b32_e32 v18, 4, v14
	v_cndmask_b32_e32 v2, v0, v2, vcc
	v_lshlrev_b32_e32 v15, 2, v2
	v_xor_b32_e32 v2, 2, v0
	v_cmp_lt_i32_e32 vcc, v2, v1
	v_lshl_add_u64 v[20:21], s[14:15], 0, v[18:19]
	v_or_b32_e32 v4, 0x180, v14
	v_cndmask_b32_e32 v2, v0, v2, vcc
	v_lshlrev_b32_e32 v40, 2, v2
	v_xor_b32_e32 v2, 4, v0
	v_cmp_lt_i32_e32 vcc, v2, v1
	v_or_b32_e32 v6, 0x1c0, v14
	s_lshl_b32 s68, s10, 3
	v_cndmask_b32_e32 v2, v0, v2, vcc
	v_lshlrev_b32_e32 v41, 2, v2
	v_xor_b32_e32 v2, 8, v0
	v_cmp_lt_i32_e32 vcc, v2, v1
	s_mov_b64 s[8:9], 0
	v_mov_b32_e32 v33, v19
	v_cndmask_b32_e32 v2, v0, v2, vcc
	v_lshlrev_b32_e32 v42, 2, v2
	v_xor_b32_e32 v2, 16, v0
	v_cmp_lt_i32_e32 vcc, v2, v1
	v_mov_b32_e32 v35, v19
	v_lshlrev_b32_e32 v36, 4, v4
	v_cndmask_b32_e32 v2, v0, v2, vcc
	v_lshlrev_b32_e32 v43, 2, v2
	v_xor_b32_e32 v2, 32, v0
	v_cmp_lt_i32_e32 vcc, v2, v1
	v_mov_b32_e32 v37, v19
	v_lshlrev_b32_e32 v38, 4, v6
	v_cndmask_b32_e32 v0, v0, v2, vcc
	v_lshlrev_b32_e32 v44, 2, v0
	v_or_b32_e32 v0, 0x100, v14
	v_or_b32_e32 v2, 0x140, v14
	v_lshlrev_b32_e32 v18, 4, v0
	v_lshl_add_u64 v[22:23], s[14:15], 0, v[18:19]
	v_lshlrev_b32_e32 v18, 4, v2
	v_lshl_add_u64 v[24:25], s[14:15], 0, v[18:19]
	v_lshlrev_b32_e32 v18, 4, v4
	v_lshl_add_u64 v[26:27], s[14:15], 0, v[18:19]
	v_lshlrev_b32_e32 v18, 4, v6
	v_lshl_add_u64 v[28:29], s[14:15], 0, v[18:19]
	v_lshlrev_b32_e32 v18, 3, v14
	v_lshl_add_u64 v[30:31], s[28:29], 0, v[18:19]
	v_lshlrev_b32_e32 v18, 4, v14
	v_lshlrev_b32_e32 v32, 4, v0
	v_lshlrev_b32_e32 v34, 4, v2
	v_mov_b32_e32 v39, v19
	v_mov_b32_e32 v45, 0x358637bd
	s_mov_b32 s14, 0xf800000
	v_mov_b32_e32 v46, 0x260
	s_movk_i32 s15, 0x7fff
	v_ashrrev_i32_e32 v17, 31, v16
	v_lshlrev_b64 v[208:209], 13, v[16:17]
	v_lshl_add_u64 v[208:209], s[12:13], 0, v[208:209]
	v_lshl_add_u64 v[210:211], v[208:209], 0, v[36:37]
	v_lshl_add_u64 v[212:213], v[208:209], 0, v[38:39]
	global_load_dwordx4 v[200:203], v[210:211], off
	global_load_dwordx4 v[204:207], v[212:213], off
	v_lshl_add_u64 v[210:211], v[208:209], 0, v[18:19]
	v_lshl_add_u64 v[212:213], v[208:209], 0, v[32:33]
	v_lshl_add_u64 v[208:209], v[208:209], 0, v[34:35]
	global_load_dwordx4 v[176:179], v[210:211], off
	global_load_dwordx4 v[180:183], v[210:211], off offset:1024
	global_load_dwordx4 v[184:187], v[210:211], off offset:2048
	global_load_dwordx4 v[188:191], v[210:211], off offset:3072
	global_load_dwordx4 v[192:195], v[212:213], off
	global_load_dwordx4 v[196:199], v[208:209], off
	global_load_dwordx4 v[140:143], v[20:21], off
	global_load_dwordx4 v[144:147], v[20:21], off offset:1024
	global_load_dwordx4 v[148:151], v[20:21], off offset:2048
	global_load_dwordx4 v[152:155], v[20:21], off offset:3072
	global_load_dwordx4 v[156:159], v[22:23], off
	global_load_dwordx4 v[160:163], v[24:25], off
	global_load_dwordx4 v[164:167], v[26:27], off
	global_load_dwordx4 v[168:171], v[28:29], off
.LBB0_21:
	s_waitcnt vmcnt(8)
	v_mov_b64_e32 v[48:49], v[176:177]
	v_mov_b64_e32 v[50:51], v[178:179]
	v_mov_b64_e32 v[52:53], v[180:181]
	v_mov_b64_e32 v[54:55], v[182:183]
	v_mov_b64_e32 v[56:57], v[184:185]
	v_mov_b64_e32 v[58:59], v[186:187]
	v_mov_b64_e32 v[60:61], v[188:189]
	v_mov_b64_e32 v[62:63], v[190:191]
	v_mov_b64_e32 v[64:65], v[192:193]
	v_mov_b64_e32 v[66:67], v[194:195]
	v_mov_b64_e32 v[8:9], v[196:197]
	v_mov_b64_e32 v[10:11], v[198:199]
	v_mov_b64_e32 v[4:5], v[200:201]
	v_mov_b64_e32 v[6:7], v[202:203]
	v_mov_b64_e32 v[0:1], v[204:205]
	v_mov_b64_e32 v[2:3], v[206:207]
	v_ashrrev_i32_e32 v17, 31, v16
	v_add_u32_e32 v208, s68, v16
	v_min_i32_e32 v208, s15, v208
	v_mov_b32_e32 v209, 0
	v_lshlrev_b64 v[208:209], 13, v[208:209]
	v_lshl_add_u64 v[208:209], s[12:13], 0, v[208:209]
	v_lshl_add_u64 v[210:211], v[208:209], 0, v[36:37]
	v_lshl_add_u64 v[212:213], v[208:209], 0, v[38:39]
	global_load_dwordx4 v[200:203], v[210:211], off
	global_load_dwordx4 v[204:207], v[212:213], off
	v_lshl_add_u64 v[210:211], v[208:209], 0, v[18:19]
	v_lshl_add_u64 v[212:213], v[208:209], 0, v[32:33]
	v_lshl_add_u64 v[208:209], v[208:209], 0, v[34:35]
	global_load_dwordx4 v[176:179], v[210:211], off
	global_load_dwordx4 v[180:183], v[210:211], off offset:1024
	global_load_dwordx4 v[184:187], v[210:211], off offset:2048
	global_load_dwordx4 v[188:191], v[210:211], off offset:3072
	global_load_dwordx4 v[192:195], v[212:213], off
	global_load_dwordx4 v[196:199], v[208:209], off
	v_mul_f32_e32 v47, v49, v49
	v_mul_f32_e32 v80, v53, v53
	v_mul_f32_e32 v81, v57, v57
	v_fmac_f32_e32 v47, v48, v48
	v_fmac_f32_e32 v80, v52, v52
	v_mul_f32_e32 v82, v61, v61
	v_fmac_f32_e32 v81, v56, v56
	v_fmac_f32_e32 v47, v50, v50
	v_fmac_f32_e32 v80, v54, v54
	v_mul_f32_e32 v83, v65, v65
	v_fmac_f32_e32 v82, v60, v60
	v_fmac_f32_e32 v81, v58, v58
	v_fmac_f32_e32 v47, v51, v51
	v_fmac_f32_e32 v80, v55, v55
	v_mov_b32_e32 v74, v5
	v_mov_b32_e32 v75, v1
	v_mul_f32_e32 v84, v9, v9
	v_fmac_f32_e32 v83, v64, v64
	v_fmac_f32_e32 v82, v62, v62
	v_fmac_f32_e32 v81, v59, v59
	v_add_f32_e32 v47, v47, v80
	v_mov_b32_e32 v72, v4
	v_mov_b32_e32 v73, v0
	v_pk_mul_f32 v[74:75], v[74:75], v[74:75]
	v_fmac_f32_e32 v84, v8, v8
	v_fmac_f32_e32 v83, v66, v66
	v_fmac_f32_e32 v82, v63, v63
	v_add_f32_e32 v47, v47, v81
	v_mov_b32_e32 v76, v6
	v_mov_b32_e32 v77, v2
	v_pk_fma_f32 v[72:73], v[72:73], v[72:73], v[74:75]
	v_fmac_f32_e32 v84, v10, v10
	v_fmac_f32_e32 v83, v67, v67
	v_add_f32_e32 v47, v47, v82
	v_mov_b32_e32 v78, v7
	v_mov_b32_e32 v79, v3
	v_pk_fma_f32 v[72:73], v[76:77], v[76:77], v[72:73]
	v_fmac_f32_e32 v84, v11, v11
	v_add_f32_e32 v47, v47, v83
	v_pk_fma_f32 v[72:73], v[78:79], v[78:79], v[72:73]
	v_add_f32_e32 v47, v47, v84
	v_add_f32_e32 v47, v47, v72
	v_add_f32_e32 v47, v47, v73
	ds_bpermute_b32 v72, v15, v47
	s_waitcnt lgkmcnt(0)
; DI unsigned pk2(float lo, float hi) { f32x2 v = {lo, hi}; bf16x2_t b = __builtin_convertvector(v, bf16x2_t); return __builtin_bit_cast(unsigned, b); }
; DI void phase_prep(const Params& P, unsigned char* smem) {
;     ...
;         s = wave_sum(s);
;         const float rstd = 1.f / sqrtf(s * (1.f / DM) + EPSF);
;         u32x2* o = (u32x2*)(P_h + (size_t)row * DM);
; #pragma unroll
;         for (int j = 0; j < 8; ++j) { const f32x4 w = ((const f32x4*)P.norm_w)[lane + 64 * j]; u32x2 r; r.x = pk2(v[j][0] * rstd * w[0], v[j][1] * rstd * w[1]); r.y = pk2(v[j][2] * rstd * w[2], v[j][3] * rstd * w[3]); o[lane + 64 * j] = r; }
	v_add_f32_e32 v47, v47, v72
	ds_bpermute_b32 v72, v40, v47
	s_waitcnt lgkmcnt(0)
	v_add_f32_e32 v47, v47, v72
	ds_bpermute_b32 v72, v41, v47
	s_waitcnt lgkmcnt(0)
	v_add_f32_e32 v47, v47, v72
	ds_bpermute_b32 v72, v42, v47
	s_waitcnt lgkmcnt(0)
	v_add_f32_e32 v47, v47, v72
	ds_bpermute_b32 v72, v43, v47
	s_waitcnt lgkmcnt(0)
	v_add_f32_e32 v47, v47, v72
	ds_bpermute_b32 v72, v44, v47
	s_waitcnt lgkmcnt(0)
	v_add_f32_e32 v47, v47, v72
	v_fmamk_f32 v47, v47, 0x3a000000, v45
	v_mul_f32_e32 v72, 0x4f800000, v47
	v_cmp_gt_f32_e32 vcc, s14, v47
	s_nop 1
	v_cndmask_b32_e32 v47, v47, v72, vcc
	v_sqrt_f32_e32 v74, v47
	v_lshlrev_b64 v[72:73], 12, v[16:17]
	v_lshl_add_u64 v[72:73], v[30:31], 0, v[72:73]
	v_add_u32_e32 v16, s68, v16
	v_add_u32_e32 v17, -1, v74
	v_add_u32_e32 v75, 1, v74
	v_fma_f32 v76, -v17, v74, v47
	v_fma_f32 v77, -v75, v74, v47
	v_cmp_ge_f32_e64 s[2:3], 0, v76
	s_nop 1
	v_cndmask_b32_e64 v17, v74, v17, s[2:3]
	v_cmp_lt_f32_e64 s[2:3], 0, v77
	s_nop 1
	v_cndmask_b32_e64 v17, v17, v75, s[2:3]
	v_mul_f32_e32 v74, 0x37800000, v17
	v_cndmask_b32_e32 v17, v17, v74, vcc
	v_cmp_class_f32_e32 vcc, v47, v46
	s_nop 1
	v_cndmask_b32_e32 v17, v17, v47, vcc
	v_div_scale_f32 v47, s[2:3], v17, v17, 1.0
	v_rcp_f32_e32 v74, v47
	v_div_scale_f32 v75, vcc, 1.0, v17, 1.0
	v_fma_f32 v76, -v47, v74, 1.0
	v_fmac_f32_e32 v74, v76, v74
	v_mul_f32_e32 v76, v75, v74
	v_fma_f32 v77, -v47, v76, v75
	v_fmac_f32_e32 v76, v77, v74
	v_fma_f32 v47, -v47, v76, v75
	v_div_fmas_f32 v47, v47, v74, v76
	v_div_fixup_f32 v74, v47, v17, 1.0
	s_waitcnt vmcnt(8)
	v_pk_mul_f32 v[48:49], v[48:49], v[74:75] op_sel_hi:[1,0]
	v_pk_mul_f32 v[50:51], v[50:51], v[74:75] op_sel_hi:[1,0]
	v_pk_mul_f32 v[48:49], v[140:141], v[48:49]
	v_pk_mul_f32 v[50:51], v[142:143], v[50:51]
	v_cvt_pk_bf16_f32 v48, v48, v49
	v_cvt_pk_bf16_f32 v49, v50, v51
	global_store_dwordx2 v[72:73], v[48:49], off
	v_pk_mul_f32 v[52:53], v[52:53], v[74:75] op_sel_hi:[1,0]
	v_pk_mul_f32 v[54:55], v[54:55], v[74:75] op_sel_hi:[1,0]
	v_pk_mul_f32 v[52:53], v[144:145], v[52:53]
	v_pk_mul_f32 v[54:55], v[146:147], v[54:55]
	v_cvt_pk_bf16_f32 v52, v52, v53
	v_cvt_pk_bf16_f32 v53, v54, v55
	global_store_dwordx2 v[72:73], v[52:53], off offset:512
	v_pk_mul_f32 v[56:57], v[56:57], v[74:75] op_sel_hi:[1,0]
	v_pk_mul_f32 v[58:59], v[58:59], v[74:75] op_sel_hi:[1,0]
	v_pk_mul_f32 v[56:57], v[148:149], v[56:57]
	v_pk_mul_f32 v[58:59], v[150:151], v[58:59]
	v_cvt_pk_bf16_f32 v56, v56, v57
	v_cvt_pk_bf16_f32 v57, v58, v59
	global_store_dwordx2 v[72:73], v[56:57], off offset:1024
	v_pk_mul_f32 v[60:61], v[60:61], v[74:75] op_sel_hi:[1,0]
	v_pk_mul_f32 v[62:63], v[62:63], v[74:75] op_sel_hi:[1,0]
	v_pk_mul_f32 v[60:61], v[152:153], v[60:61]
	v_pk_mul_f32 v[62:63], v[154:155], v[62:63]
	v_cvt_pk_bf16_f32 v60, v60, v61
	v_cvt_pk_bf16_f32 v61, v62, v63
	global_store_dwordx2 v[72:73], v[60:61], off offset:1536
	v_pk_mul_f32 v[64:65], v[64:65], v[74:75] op_sel_hi:[1,0]
	v_pk_mul_f32 v[66:67], v[66:67], v[74:75] op_sel_hi:[1,0]
	v_pk_mul_f32 v[64:65], v[156:157], v[64:65]
	v_pk_mul_f32 v[66:67], v[158:159], v[66:67]
	v_cvt_pk_bf16_f32 v64, v64, v65
	v_cvt_pk_bf16_f32 v65, v66, v67
	global_store_dwordx2 v[72:73], v[64:65], off offset:2048
	v_pk_mul_f32 v[8:9], v[8:9], v[74:75] op_sel_hi:[1,0]
	v_pk_mul_f32 v[10:11], v[10:11], v[74:75] op_sel_hi:[1,0]
	v_pk_mul_f32 v[8:9], v[160:161], v[8:9]
	v_pk_mul_f32 v[10:11], v[162:163], v[10:11]
	v_cvt_pk_bf16_f32 v8, v8, v9
	v_cvt_pk_bf16_f32 v9, v10, v11
	global_store_dwordx2 v[72:73], v[8:9], off offset:2560
	v_pk_mul_f32 v[4:5], v[4:5], v[74:75] op_sel_hi:[1,0]
	v_pk_mul_f32 v[6:7], v[6:7], v[74:75] op_sel_hi:[1,0]
	v_pk_mul_f32 v[4:5], v[164:165], v[4:5]
	v_pk_mul_f32 v[6:7], v[166:167], v[6:7]
	v_cvt_pk_bf16_f32 v4, v4, v5
	v_cvt_pk_bf16_f32 v5, v6, v7
	global_store_dwordx2 v[72:73], v[4:5], off offset:3072
	v_pk_mul_f32 v[0:1], v[0:1], v[74:75] op_sel_hi:[1,0]
	v_pk_mul_f32 v[2:3], v[2:3], v[74:75] op_sel_hi:[1,0]
	v_pk_mul_f32 v[0:1], v[168:169], v[0:1]
	v_pk_mul_f32 v[2:3], v[170:171], v[2:3]
	v_cvt_pk_bf16_f32 v0, v0, v1
	v_cvt_pk_bf16_f32 v1, v2, v3
	global_store_dwordx2 v[72:73], v[0:1], off offset:3584
	v_cmp_lt_i32_e32 vcc, s15, v16
	s_or_b64 s[8:9], vcc, s[8:9]
	s_andn2_b64 exec, exec, s[8:9]
	s_cbranch_execnz .LBB0_21
